# attention inner loop: PV split per score map, map0 PV MFMAs interleaved with map1 softmax VALU, V fragments read during map0 softmax
# speedup vs baseline: 1.0168x; 1.0032x over previous
; #define LAS __attribute__((address_space(3)))
; __device__ __forceinline__ void dattn_unit(LAS unsigned char* lds, int b, int h, int qb, const bf16* Q, const bf16* K, const bf16* V, bf16* YB, float lam, const float* subg, float oml, int tid) {
;     ...
;             AT_SOFTMAX(s0, 0, pA0, pB0);
;             AT_SOFTMAX(s1, 1, pA1, pB1);
; #pragma unroll
;             for (int cb = 0; cb < 4; ++cb) { const LAS bf16* vp = Vt + (32 * cb + ql) * 72 + 32 * sub + 4 * hi;
;                 const v2u a0 = *(const LAS v2u*)(vp), a1 = *(const LAS v2u*)(vp + 8), a2 = *(const LAS v2u*)(vp + 16), a3 = *(const LAS v2u*)(vp + 24);
;                 const v4u f0 = {a0.x, a0.y, a1.x, a1.y}, f1 = {a2.x, a2.y, a3.x, a3.y};
;                 o[0][cb] = __builtin_amdgcn_mfma_f32_32x32x16_bf16(__builtin_bit_cast(bf16x8, f0), pA0, o[0][cb], 0, 0, 0);
;                 o[1][cb] = __builtin_amdgcn_mfma_f32_32x32x16_bf16(__builtin_bit_cast(bf16x8, f0), pA1, o[1][cb], 0, 0, 0);
;                 o[0][cb] = __builtin_amdgcn_mfma_f32_32x32x16_bf16(__builtin_bit_cast(bf16x8, f1), pB0, o[0][cb], 0, 0, 0);
;                 o[1][cb] = __builtin_amdgcn_mfma_f32_32x32x16_bf16(__builtin_bit_cast(bf16x8, f1), pB1, o[1][cb], 0, 0, 0); }
.LBB0_230:
	v_add_u32_e32 v219, s38, v193
	v_add_u32_e32 v219, v219, v192
	v_add_u32_e32 v224, 0x5800, v219
	v_add_u32_e32 v200, 0x7800, v219
	ds_read2_b64 v[228:231], v224 offset0:64 offset1:66
	ds_read2_b64 v[232:235], v224 offset0:68 offset1:70
	v_add_u32_e32 v224, 0x6800, v219
	ds_read2_b64 v[236:239], v224 offset0:128 offset1:130
	ds_read2_b64 v[240:243], v224 offset0:132 offset1:134
	ds_read2_b64 v[212:215], v200 offset0:192 offset1:194
	v_add_u32_e32 v219, 0x4800, v219
	ds_read2_b64 v[220:223], v219 offset1:2
	v_exp_f32_e32 v201, v144
	v_exp_f32_e32 v202, v145
	v_exp_f32_e32 v203, v146
	v_exp_f32_e32 v204, v147
	v_add_f32_e32 v144, 0, v201
	v_exp_f32_e32 v205, v148
	v_add_f32_e32 v144, v202, v144
	v_exp_f32_e32 v206, v149
	v_add_f32_e32 v144, v203, v144
	v_exp_f32_e32 v207, v150
	v_add_f32_e32 v144, v204, v144
	v_exp_f32_e32 v218, v151
	v_add_f32_e32 v144, v205, v144
	v_exp_f32_e32 v147, v152
	v_add_f32_e32 v144, v206, v144
	v_exp_f32_e32 v148, v153
	v_add_f32_e32 v144, v207, v144
	v_exp_f32_e32 v149, v154
	v_add_f32_e32 v144, v218, v144
	v_exp_f32_e32 v150, v155
	v_add_f32_e32 v144, v147, v144
	v_exp_f32_e32 v151, v156
	v_add_f32_e32 v144, v148, v144
	v_exp_f32_e32 v152, v157
	v_add_f32_e32 v144, v149, v144
	v_exp_f32_e32 v153, v158
	v_add_f32_e32 v144, v150, v144
	v_exp_f32_e32 v154, v159
	v_add_f32_e32 v144, v151, v144
	v_add_f32_e32 v144, v152, v144
	v_add_f32_e32 v144, v153, v144
	v_add_f32_e32 v145, v154, v144
	v_cmp_lt_f32_e32 vcc, s82, v145
	s_cmp_lg_u64 vcc, 0
	v_mov_b32_e32 v144, 1.0
	s_cselect_b64 s[48:49], -1, 0
	v_mov_b32_e32 v146, 1.0
	s_cbranch_vccz .LBB0_232
	v_max_f32_e32 v146, v204, v204
	v_max_f32_e32 v155, v203, v203
	v_max_f32_e32 v146, v155, v146
	v_max_f32_e32 v155, v218, v218
	v_max_f32_e32 v156, v207, v207
	v_max_f32_e32 v155, v156, v155
	v_max_f32_e32 v156, v148, v148
	v_max_f32_e32 v157, v147, v147
	v_max_f32_e32 v156, v157, v156
	v_max_f32_e32 v157, v150, v150
	v_max_f32_e32 v158, v149, v149
	v_max_f32_e32 v157, v158, v157
	v_max_f32_e32 v158, v154, v154
	v_max_f32_e32 v159, v153, v153
	v_max_f32_e32 v158, v159, v158
	v_max3_f32 v158, v151, v152, v158
	v_max3_f32 v146, v201, v202, v146
	v_max3_f32 v155, v205, v206, v155
	v_max3_f32 v156, v156, v157, v158
	v_max3_f32 v146, v146, v155, v156
	v_mov_b32_e32 v155, v146
	s_nop 1
	v_permlane32_swap_b32_e32 v146, v155
	v_max_f32_e32 v155, v155, v155
	v_max_f32_e32 v146, v146, v146
	v_max_f32_e32 v146, v146, v155
.LBB0_232:
	v_cvt_pk_bf16_f32 v224, v201, v202
	v_cvt_pk_bf16_f32 v225, v203, v204
	v_cvt_pk_bf16_f32 v226, v205, v206
	v_cvt_pk_bf16_f32 v227, v207, v218
	v_cvt_pk_bf16_f32 v148, v147, v148
	v_cvt_pk_bf16_f32 v149, v149, v150
	v_cvt_pk_bf16_f32 v150, v151, v152
	v_cvt_pk_bf16_f32 v151, v153, v154
	ds_read2_b64 v[204:207], v219 offset0:4 offset1:6
	ds_read2_b64 v[200:203], v200 offset0:196 offset1:198
	v_add_f32_e32 v179, v179, v145
	v_exp_f32_e32 v155, v128
	v_exp_f32_e32 v129, v129
	v_exp_f32_e32 v130, v130
	v_exp_f32_e32 v131, v131
	s_waitcnt lgkmcnt(2)
	v_mfma_f32_32x32x16_bf16 v[80:95], v[228:231], v[224:227], v[80:95]
	v_add_f32_e32 v128, 0, v155
	v_exp_f32_e32 v132, v132
	v_add_f32_e32 v128, v129, v128
	v_exp_f32_e32 v156, v133
	v_mfma_f32_32x32x16_bf16 v[80:95], v[232:235], v[148:151], v[80:95]
	v_add_f32_e32 v128, v130, v128
	v_exp_f32_e32 v157, v134
	v_add_f32_e32 v128, v131, v128
	v_exp_f32_e32 v158, v135
	v_mfma_f32_32x32x16_bf16 v[48:63], v[236:239], v[224:227], v[48:63]
	v_add_f32_e32 v128, v132, v128
	v_exp_f32_e32 v133, v136
	v_add_f32_e32 v128, v156, v128
	v_exp_f32_e32 v134, v137
	v_mfma_f32_32x32x16_bf16 v[48:63], v[240:243], v[148:151], v[48:63]
	v_add_f32_e32 v128, v157, v128
	v_exp_f32_e32 v135, v138
	v_add_f32_e32 v128, v158, v128
	v_exp_f32_e32 v136, v139
	v_mfma_f32_32x32x16_bf16 v[16:31], v[212:215], v[224:227], v[16:31]
	v_add_f32_e32 v128, v133, v128
	v_exp_f32_e32 v137, v140
	v_add_f32_e32 v128, v134, v128
	v_exp_f32_e32 v138, v141
	v_mfma_f32_32x32x16_bf16 v[112:127], v[220:223], v[224:227], v[112:127]
	v_add_f32_e32 v128, v135, v128
	v_exp_f32_e32 v139, v142
	v_add_f32_e32 v128, v136, v128
	v_exp_f32_e32 v140, v143
	s_waitcnt lgkmcnt(1)
	v_mfma_f32_32x32x16_bf16 v[112:127], v[204:207], v[148:151], v[112:127]
	v_add_f32_e32 v128, v137, v128
	v_add_f32_e32 v128, v138, v128
	v_add_f32_e32 v128, v139, v128
	v_add_f32_e32 v128, v140, v128
	s_waitcnt lgkmcnt(0)
	v_mfma_f32_32x32x16_bf16 v[16:31], v[200:203], v[148:151], v[16:31]
	v_cmp_lt_f32_e32 vcc, s82, v128
	s_cmp_lg_u64 vcc, 0
	s_cselect_b64 s[46:47], -1, 0
	s_cbranch_vccz .LBB0_234
	v_max_f32_e32 v141, v131, v131
	v_max_f32_e32 v142, v130, v130
	v_max_f32_e32 v141, v142, v141
	v_max_f32_e32 v142, v158, v158
	v_max_f32_e32 v143, v157, v157
	v_max_f32_e32 v142, v143, v142
	v_max_f32_e32 v143, v134, v134
	v_max_f32_e32 v144, v133, v133
	v_max_f32_e32 v143, v144, v143
	v_max_f32_e32 v144, v136, v136
	v_max_f32_e32 v159, v135, v135
	v_max_f32_e32 v144, v159, v144
	v_max_f32_e32 v159, v140, v140
	v_max_f32_e32 v147, v139, v139
	v_max_f32_e32 v159, v147, v159
	v_max3_f32 v159, v137, v138, v159
	v_max3_f32 v141, v155, v129, v141
	v_max3_f32 v142, v132, v156, v142
	v_max3_f32 v143, v143, v144, v159
	v_max3_f32 v141, v141, v142, v143
	v_mov_b32_e32 v142, v141
	s_nop 1
	v_permlane32_swap_b32_e32 v141, v142
	v_max_f32_e32 v142, v142, v142
	v_max_f32_e32 v141, v141, v141
	v_max_f32_e32 v144, v141, v142
; #define LAS __attribute__((address_space(3)))
; #define AT_RAISE(MP) do { if (trig[MP]) { const float dl = fmaxf(__builtin_amdgcn_logf(pmx[MP]), 0.f), al = __builtin_amdgcn_exp2f(-dl); mref[MP] += dl; lsum[MP] *= al; \
;                 _Pragma("unroll") for (int cb = 0; cb < 4; ++cb) o[MP][cb] = o[MP][cb] * al; } } while (0)
; __device__ __forceinline__ void dattn_unit(LAS unsigned char* lds, int b, int h, int qb, const bf16* Q, const bf16* K, const bf16* V, bf16* YB, float lam, const float* subg, float oml, int tid) {
;     ...
;             for (int cb = 0; cb < 4; ++cb) { const LAS bf16* vp = Vt + (32 * cb + ql) * 72 + 32 * sub + 4 * hi;
;                 const v2u a0 = *(const LAS v2u*)(vp), a1 = *(const LAS v2u*)(vp + 8), a2 = *(const LAS v2u*)(vp + 16), a3 = *(const LAS v2u*)(vp + 24);
;                 const v4u f0 = {a0.x, a0.y, a1.x, a1.y}, f1 = {a2.x, a2.y, a3.x, a3.y};
;                 o[0][cb] = __builtin_amdgcn_mfma_f32_32x32x16_bf16(__builtin_bit_cast(bf16x8, f0), pA0, o[0][cb], 0, 0, 0);
;                 o[1][cb] = __builtin_amdgcn_mfma_f32_32x32x16_bf16(__builtin_bit_cast(bf16x8, f0), pA1, o[1][cb], 0, 0, 0);
;                 o[0][cb] = __builtin_amdgcn_mfma_f32_32x32x16_bf16(__builtin_bit_cast(bf16x8, f1), pB0, o[0][cb], 0, 0, 0);
;                 o[1][cb] = __builtin_amdgcn_mfma_f32_32x32x16_bf16(__builtin_bit_cast(bf16x8, f1), pB1, o[1][cb], 0, 0, 0); }
;             AT_RAISE(0); AT_RAISE(1);
.LBB0_234:
	v_cvt_pk_bf16_f32 v152, v155, v129
	v_cvt_pk_bf16_f32 v153, v130, v131
	v_cvt_pk_bf16_f32 v154, v132, v156
	v_cvt_pk_bf16_f32 v155, v157, v158
	v_cvt_pk_bf16_f32 v130, v133, v134
	v_cvt_pk_bf16_f32 v131, v135, v136
	v_cvt_pk_bf16_f32 v132, v137, v138
	v_cvt_pk_bf16_f32 v133, v139, v140
	s_andn2_b64 vcc, exec, s[48:49]
	s_nop 0
	v_mfma_f32_32x32x16_bf16 v[64:79], v[228:231], v[152:155], v[64:79]
	v_mfma_f32_32x32x16_bf16 v[64:79], v[232:235], v[130:133], v[64:79]
	v_mfma_f32_32x32x16_bf16 v[32:47], v[236:239], v[152:155], v[32:47]
	v_mfma_f32_32x32x16_bf16 v[32:47], v[240:243], v[130:133], v[32:47]
	v_mfma_f32_32x32x16_bf16 v[96:111], v[220:223], v[152:155], v[96:111]
	v_mfma_f32_32x32x16_bf16 v[96:111], v[204:207], v[130:133], v[96:111]
	v_mfma_f32_32x32x16_bf16 v[0:15], v[212:215], v[152:155], v[0:15]
	s_nop 0
	v_mfma_f32_32x32x16_bf16 v[0:15], v[200:203], v[130:133], v[0:15]
	s_cbranch_vccnz .LBB0_236
	v_log_f32_e32 v129, v146
	s_nop 0
	v_max_f32_e32 v129, 0, v129
	v_exp_f32_e64 v130, -v129
	v_add_f32_e32 v190, v190, v129
	s_nop 1
	v_pk_mul_f32 v[126:127], v[130:131], v[126:127] op_sel_hi:[0,1]
	v_pk_mul_f32 v[124:125], v[130:131], v[124:125] op_sel_hi:[0,1]
	v_pk_mul_f32 v[122:123], v[130:131], v[122:123] op_sel_hi:[0,1]
	v_pk_mul_f32 v[120:121], v[130:131], v[120:121] op_sel_hi:[0,1]
	v_pk_mul_f32 v[118:119], v[130:131], v[118:119] op_sel_hi:[0,1]
	v_pk_mul_f32 v[116:117], v[130:131], v[116:117] op_sel_hi:[0,1]
	v_pk_mul_f32 v[114:115], v[130:131], v[114:115] op_sel_hi:[0,1]
	v_pk_mul_f32 v[112:113], v[130:131], v[112:113] op_sel_hi:[0,1]
	v_pk_mul_f32 v[94:95], v[130:131], v[94:95] op_sel_hi:[0,1]
	v_pk_mul_f32 v[92:93], v[130:131], v[92:93] op_sel_hi:[0,1]
	v_pk_mul_f32 v[90:91], v[130:131], v[90:91] op_sel_hi:[0,1]
	v_pk_mul_f32 v[88:89], v[130:131], v[88:89] op_sel_hi:[0,1]
	v_pk_mul_f32 v[86:87], v[130:131], v[86:87] op_sel_hi:[0,1]
	v_pk_mul_f32 v[84:85], v[130:131], v[84:85] op_sel_hi:[0,1]
	v_pk_mul_f32 v[82:83], v[130:131], v[82:83] op_sel_hi:[0,1]
	v_pk_mul_f32 v[80:81], v[130:131], v[80:81] op_sel_hi:[0,1]
	v_pk_mul_f32 v[62:63], v[130:131], v[62:63] op_sel_hi:[0,1]
	v_pk_mul_f32 v[60:61], v[130:131], v[60:61] op_sel_hi:[0,1]
	v_pk_mul_f32 v[58:59], v[130:131], v[58:59] op_sel_hi:[0,1]
	v_pk_mul_f32 v[56:57], v[130:131], v[56:57] op_sel_hi:[0,1]
	v_pk_mul_f32 v[54:55], v[130:131], v[54:55] op_sel_hi:[0,1]
	v_pk_mul_f32 v[52:53], v[130:131], v[52:53] op_sel_hi:[0,1]
	v_pk_mul_f32 v[50:51], v[130:131], v[50:51] op_sel_hi:[0,1]
	v_pk_mul_f32 v[48:49], v[130:131], v[48:49] op_sel_hi:[0,1]
	v_pk_mul_f32 v[30:31], v[130:131], v[30:31] op_sel_hi:[0,1]
	v_pk_mul_f32 v[28:29], v[130:131], v[28:29] op_sel_hi:[0,1]
	v_pk_mul_f32 v[26:27], v[130:131], v[26:27] op_sel_hi:[0,1]
	v_pk_mul_f32 v[24:25], v[130:131], v[24:25] op_sel_hi:[0,1]
	v_pk_mul_f32 v[22:23], v[130:131], v[22:23] op_sel_hi:[0,1]
	v_pk_mul_f32 v[20:21], v[130:131], v[20:21] op_sel_hi:[0,1]
	v_pk_mul_f32 v[18:19], v[130:131], v[18:19] op_sel_hi:[0,1]
	v_pk_mul_f32 v[16:17], v[130:131], v[16:17] op_sel_hi:[0,1]
	v_mul_f32_e32 v179, v179, v130

; #define LAS __attribute__((address_space(3)))
; __device__ __forceinline__ void dattn_unit(LAS unsigned char* lds, int b, int h, int qb, const bf16* Q, const bf16* K, const bf16* V, bf16* YB, float lam, const float* subg, float oml, int tid) {
;     ...
;             AT_SOFTMAX(s0, 0, pA0, pB0);
;             AT_SOFTMAX(s1, 1, pA1, pB1);
; #pragma unroll
;             for (int cb = 0; cb < 4; ++cb) { const LAS bf16* vp = Vt + (32 * cb + ql) * 72 + 32 * sub + 4 * hi;
;                 const v2u a0 = *(const LAS v2u*)(vp), a1 = *(const LAS v2u*)(vp + 8), a2 = *(const LAS v2u*)(vp + 16), a3 = *(const LAS v2u*)(vp + 24);
;                 const v4u f0 = {a0.x, a0.y, a1.x, a1.y}, f1 = {a2.x, a2.y, a3.x, a3.y};
;                 o[0][cb] = __builtin_amdgcn_mfma_f32_32x32x16_bf16(__builtin_bit_cast(bf16x8, f0), pA0, o[0][cb], 0, 0, 0);
;                 o[1][cb] = __builtin_amdgcn_mfma_f32_32x32x16_bf16(__builtin_bit_cast(bf16x8, f0), pA1, o[1][cb], 0, 0, 0);
;                 o[0][cb] = __builtin_amdgcn_mfma_f32_32x32x16_bf16(__builtin_bit_cast(bf16x8, f1), pB0, o[0][cb], 0, 0, 0);
;                 o[1][cb] = __builtin_amdgcn_mfma_f32_32x32x16_bf16(__builtin_bit_cast(bf16x8, f1), pB1, o[1][cb], 0, 0, 0); }
.LBB0_241:
	v_add_u32_e32 v221, s38, v193
	v_add_u32_e32 v221, v221, v192
	v_add_u32_e32 v242, 0x5800, v221
	v_add_u32_e32 v243, 0x7800, v221
	ds_read2_b64 v[222:225], v242 offset0:72 offset1:74
	ds_read2_b64 v[226:229], v242 offset0:76 offset1:78
	v_add_u32_e32 v242, 0x6800, v221
	ds_read2_b64 v[230:233], v242 offset0:136 offset1:138
	ds_read2_b64 v[234:237], v242 offset0:140 offset1:142
	ds_read2_b64 v[238:241], v243 offset0:200 offset1:202
	v_add_u32_e32 v242, 0x4800, v221
	ds_read2_b64 v[212:215], v242 offset0:8 offset1:10
	ds_read2_b64 v[200:203], v242 offset0:12 offset1:14
	v_exp_f32_e32 v199, v144
	v_exp_f32_e32 v204, v145
	v_exp_f32_e32 v205, v146
	v_exp_f32_e32 v206, v147
	v_add_f32_e32 v144, 0, v199
	v_exp_f32_e32 v207, v148
	v_add_f32_e32 v144, v204, v144
	v_exp_f32_e32 v218, v149
	v_add_f32_e32 v144, v205, v144
	v_exp_f32_e32 v219, v150
	v_add_f32_e32 v144, v206, v144
	v_exp_f32_e32 v220, v151
	v_add_f32_e32 v144, v207, v144
	v_exp_f32_e32 v147, v152
	v_add_f32_e32 v144, v218, v144
	v_exp_f32_e32 v148, v153
	v_add_f32_e32 v144, v219, v144
	v_exp_f32_e32 v149, v154
	v_add_f32_e32 v144, v220, v144
	v_exp_f32_e32 v150, v155
	v_add_f32_e32 v144, v147, v144
	v_exp_f32_e32 v151, v156
	v_add_f32_e32 v144, v148, v144
	v_exp_f32_e32 v152, v157
	v_add_f32_e32 v144, v149, v144
	v_exp_f32_e32 v153, v158
	v_add_f32_e32 v144, v150, v144
	v_exp_f32_e32 v154, v159
	v_add_f32_e32 v144, v151, v144
	v_add_f32_e32 v144, v152, v144
	v_add_f32_e32 v144, v153, v144
	v_add_f32_e32 v145, v154, v144
	v_cmp_lt_f32_e32 vcc, s82, v145
	s_cmp_lg_u64 vcc, 0
	v_mov_b32_e32 v144, 1.0
	s_cselect_b64 s[48:49], -1, 0
	v_mov_b32_e32 v146, 1.0
	s_cbranch_vccz .LBB0_243
	v_max_f32_e32 v146, v206, v206
	v_max_f32_e32 v155, v205, v205
	v_max_f32_e32 v146, v155, v146
	v_max_f32_e32 v155, v220, v220
	v_max_f32_e32 v156, v219, v219
	v_max_f32_e32 v155, v156, v155
	v_max_f32_e32 v156, v148, v148
	v_max_f32_e32 v157, v147, v147
	v_max_f32_e32 v156, v157, v156
	v_max_f32_e32 v157, v150, v150
	v_max_f32_e32 v158, v149, v149
	v_max_f32_e32 v157, v158, v157
	v_max_f32_e32 v158, v154, v154
	v_max_f32_e32 v159, v153, v153
	v_max_f32_e32 v158, v159, v158
	v_max3_f32 v158, v151, v152, v158
	v_max3_f32 v146, v199, v204, v146
	v_max3_f32 v155, v207, v218, v155
	v_max3_f32 v156, v156, v157, v158
	v_max3_f32 v146, v146, v155, v156
	v_mov_b32_e32 v155, v146
	s_nop 1
	v_permlane32_swap_b32_e32 v146, v155
	v_max_f32_e32 v155, v155, v155
	v_max_f32_e32 v146, v146, v146
	v_max_f32_e32 v146, v146, v155
.LBB0_243:
	v_cvt_pk_bf16_f32 v205, v205, v206
	v_cvt_pk_bf16_f32 v206, v207, v218
	v_cvt_pk_bf16_f32 v207, v219, v220
	v_cvt_pk_bf16_f32 v204, v199, v204
	v_cvt_pk_bf16_f32 v148, v147, v148
	v_cvt_pk_bf16_f32 v149, v149, v150
	v_cvt_pk_bf16_f32 v150, v151, v152
	v_cvt_pk_bf16_f32 v151, v153, v154
	ds_read2_b64 v[218:221], v243 offset0:204 offset1:206
	v_add_f32_e32 v179, v179, v145
	v_exp_f32_e32 v155, v128
	v_exp_f32_e32 v129, v129
	v_exp_f32_e32 v130, v130
	v_exp_f32_e32 v131, v131
	s_waitcnt lgkmcnt(1)
	v_mfma_f32_32x32x16_bf16 v[80:95], v[222:225], v[204:207], v[80:95]
	v_add_f32_e32 v128, 0, v155
	v_exp_f32_e32 v132, v132
	v_add_f32_e32 v128, v129, v128
	v_exp_f32_e32 v156, v133
	v_mfma_f32_32x32x16_bf16 v[80:95], v[226:229], v[148:151], v[80:95]
	v_add_f32_e32 v128, v130, v128
	v_exp_f32_e32 v157, v134
	v_add_f32_e32 v128, v131, v128
	v_exp_f32_e32 v158, v135
	v_mfma_f32_32x32x16_bf16 v[48:63], v[230:233], v[204:207], v[48:63]
	v_add_f32_e32 v128, v132, v128
	v_exp_f32_e32 v133, v136
	v_add_f32_e32 v128, v156, v128
	v_exp_f32_e32 v134, v137
	v_mfma_f32_32x32x16_bf16 v[48:63], v[234:237], v[148:151], v[48:63]
	v_add_f32_e32 v128, v157, v128
	v_exp_f32_e32 v135, v138
	v_add_f32_e32 v128, v158, v128
	v_exp_f32_e32 v136, v139
	v_mfma_f32_32x32x16_bf16 v[16:31], v[238:241], v[204:207], v[16:31]
	v_add_f32_e32 v128, v133, v128
	v_exp_f32_e32 v137, v140
	v_add_f32_e32 v128, v134, v128
	v_exp_f32_e32 v138, v141
	v_mfma_f32_32x32x16_bf16 v[112:127], v[212:215], v[204:207], v[112:127]
	v_add_f32_e32 v128, v135, v128
	v_exp_f32_e32 v139, v142
	v_add_f32_e32 v128, v136, v128
	v_exp_f32_e32 v140, v143
	v_mfma_f32_32x32x16_bf16 v[112:127], v[200:203], v[148:151], v[112:127]
	v_add_f32_e32 v128, v137, v128
	v_add_f32_e32 v128, v138, v128
	v_add_f32_e32 v128, v139, v128
	v_add_f32_e32 v128, v140, v128
	s_waitcnt lgkmcnt(0)
	v_mfma_f32_32x32x16_bf16 v[16:31], v[218:221], v[148:151], v[16:31]
	v_cmp_lt_f32_e32 vcc, s82, v128
	s_cmp_lg_u64 vcc, 0
	s_cselect_b64 s[46:47], -1, 0
	s_cbranch_vccz .LBB0_245
	v_max_f32_e32 v141, v131, v131
	v_max_f32_e32 v142, v130, v130
	v_max_f32_e32 v141, v142, v141
	v_max_f32_e32 v142, v158, v158
	v_max_f32_e32 v143, v157, v157
	v_max_f32_e32 v142, v143, v142
	v_max_f32_e32 v143, v134, v134
	v_max_f32_e32 v144, v133, v133
	v_max_f32_e32 v143, v144, v143
	v_max_f32_e32 v144, v136, v136
	v_max_f32_e32 v159, v135, v135
	v_max_f32_e32 v144, v159, v144
	v_max_f32_e32 v159, v140, v140
	v_max_f32_e32 v147, v139, v139
	v_max_f32_e32 v159, v147, v159
	v_max3_f32 v159, v137, v138, v159
	v_max3_f32 v141, v155, v129, v141
	v_max3_f32 v142, v132, v156, v142
	v_max3_f32 v143, v143, v144, v159
	v_max3_f32 v141, v141, v142, v143
	v_mov_b32_e32 v142, v141
	s_nop 1
	v_permlane32_swap_b32_e32 v141, v142
	v_max_f32_e32 v142, v142, v142
	v_max_f32_e32 v141, v141, v141
	v_max_f32_e32 v144, v141, v142
; #define LAS __attribute__((address_space(3)))
; #define AT_RAISE(MP) do { if (trig[MP]) { const float dl = fmaxf(__builtin_amdgcn_logf(pmx[MP]), 0.f), al = __builtin_amdgcn_exp2f(-dl); mref[MP] += dl; lsum[MP] *= al; \
;                 _Pragma("unroll") for (int cb = 0; cb < 4; ++cb) o[MP][cb] = o[MP][cb] * al; } } while (0)
; __device__ __forceinline__ void dattn_unit(LAS unsigned char* lds, int b, int h, int qb, const bf16* Q, const bf16* K, const bf16* V, bf16* YB, float lam, const float* subg, float oml, int tid) {
;     ...
;             for (int cb = 0; cb < 4; ++cb) { const LAS bf16* vp = Vt + (32 * cb + ql) * 72 + 32 * sub + 4 * hi;
;                 const v2u a0 = *(const LAS v2u*)(vp), a1 = *(const LAS v2u*)(vp + 8), a2 = *(const LAS v2u*)(vp + 16), a3 = *(const LAS v2u*)(vp + 24);
;                 const v4u f0 = {a0.x, a0.y, a1.x, a1.y}, f1 = {a2.x, a2.y, a3.x, a3.y};
;                 o[0][cb] = __builtin_amdgcn_mfma_f32_32x32x16_bf16(__builtin_bit_cast(bf16x8, f0), pA0, o[0][cb], 0, 0, 0);
;                 o[1][cb] = __builtin_amdgcn_mfma_f32_32x32x16_bf16(__builtin_bit_cast(bf16x8, f0), pA1, o[1][cb], 0, 0, 0);
;                 o[0][cb] = __builtin_amdgcn_mfma_f32_32x32x16_bf16(__builtin_bit_cast(bf16x8, f1), pB0, o[0][cb], 0, 0, 0);
;                 o[1][cb] = __builtin_amdgcn_mfma_f32_32x32x16_bf16(__builtin_bit_cast(bf16x8, f1), pB1, o[1][cb], 0, 0, 0); }
;             AT_RAISE(0); AT_RAISE(1);
.LBB0_245:
	v_cvt_pk_bf16_f32 v152, v155, v129
	v_cvt_pk_bf16_f32 v153, v130, v131
	v_cvt_pk_bf16_f32 v154, v132, v156
	v_cvt_pk_bf16_f32 v155, v157, v158
	v_cvt_pk_bf16_f32 v130, v133, v134
	v_cvt_pk_bf16_f32 v131, v135, v136
	v_cvt_pk_bf16_f32 v132, v137, v138
	v_cvt_pk_bf16_f32 v133, v139, v140
	s_andn2_b64 vcc, exec, s[48:49]
	s_nop 0
	v_mfma_f32_32x32x16_bf16 v[64:79], v[222:225], v[152:155], v[64:79]
	v_mfma_f32_32x32x16_bf16 v[64:79], v[226:229], v[130:133], v[64:79]
	v_mfma_f32_32x32x16_bf16 v[32:47], v[230:233], v[152:155], v[32:47]
	v_mfma_f32_32x32x16_bf16 v[32:47], v[234:237], v[130:133], v[32:47]
	v_mfma_f32_32x32x16_bf16 v[96:111], v[212:215], v[152:155], v[96:111]
	v_mfma_f32_32x32x16_bf16 v[96:111], v[200:203], v[130:133], v[96:111]
	v_mfma_f32_32x32x16_bf16 v[0:15], v[238:241], v[152:155], v[0:15]
	s_nop 0
	v_mfma_f32_32x32x16_bf16 v[0:15], v[218:221], v[130:133], v[0:15]
	s_cbranch_vccnz .LBB0_247
	v_log_f32_e32 v129, v146
	s_nop 0
	v_max_f32_e32 v129, 0, v129
	v_exp_f32_e64 v130, -v129
	v_add_f32_e32 v190, v190, v129
	s_nop 1
	v_pk_mul_f32 v[126:127], v[130:131], v[126:127] op_sel_hi:[0,1]
	v_pk_mul_f32 v[124:125], v[130:131], v[124:125] op_sel_hi:[0,1]
	v_pk_mul_f32 v[122:123], v[130:131], v[122:123] op_sel_hi:[0,1]
	v_pk_mul_f32 v[120:121], v[130:131], v[120:121] op_sel_hi:[0,1]
	v_pk_mul_f32 v[118:119], v[130:131], v[118:119] op_sel_hi:[0,1]
	v_pk_mul_f32 v[116:117], v[130:131], v[116:117] op_sel_hi:[0,1]
	v_pk_mul_f32 v[114:115], v[130:131], v[114:115] op_sel_hi:[0,1]
	v_pk_mul_f32 v[112:113], v[130:131], v[112:113] op_sel_hi:[0,1]
	v_pk_mul_f32 v[94:95], v[130:131], v[94:95] op_sel_hi:[0,1]
	v_pk_mul_f32 v[92:93], v[130:131], v[92:93] op_sel_hi:[0,1]
	v_pk_mul_f32 v[90:91], v[130:131], v[90:91] op_sel_hi:[0,1]
	v_pk_mul_f32 v[88:89], v[130:131], v[88:89] op_sel_hi:[0,1]
	v_pk_mul_f32 v[86:87], v[130:131], v[86:87] op_sel_hi:[0,1]
	v_pk_mul_f32 v[84:85], v[130:131], v[84:85] op_sel_hi:[0,1]
	v_pk_mul_f32 v[82:83], v[130:131], v[82:83] op_sel_hi:[0,1]
	v_pk_mul_f32 v[80:81], v[130:131], v[80:81] op_sel_hi:[0,1]
	v_pk_mul_f32 v[62:63], v[130:131], v[62:63] op_sel_hi:[0,1]
	v_pk_mul_f32 v[60:61], v[130:131], v[60:61] op_sel_hi:[0,1]
	v_pk_mul_f32 v[58:59], v[130:131], v[58:59] op_sel_hi:[0,1]
	v_pk_mul_f32 v[56:57], v[130:131], v[56:57] op_sel_hi:[0,1]
	v_pk_mul_f32 v[54:55], v[130:131], v[54:55] op_sel_hi:[0,1]
	v_pk_mul_f32 v[52:53], v[130:131], v[52:53] op_sel_hi:[0,1]
	v_pk_mul_f32 v[50:51], v[130:131], v[50:51] op_sel_hi:[0,1]
	v_pk_mul_f32 v[48:49], v[130:131], v[48:49] op_sel_hi:[0,1]
	v_pk_mul_f32 v[30:31], v[130:131], v[30:31] op_sel_hi:[0,1]
	v_pk_mul_f32 v[28:29], v[130:131], v[28:29] op_sel_hi:[0,1]
	v_pk_mul_f32 v[26:27], v[130:131], v[26:27] op_sel_hi:[0,1]
	v_pk_mul_f32 v[24:25], v[130:131], v[24:25] op_sel_hi:[0,1]
	v_pk_mul_f32 v[22:23], v[130:131], v[22:23] op_sel_hi:[0,1]
	v_pk_mul_f32 v[20:21], v[130:131], v[20:21] op_sel_hi:[0,1]
	v_pk_mul_f32 v[18:19], v[130:131], v[18:19] op_sel_hi:[0,1]
	v_pk_mul_f32 v[16:17], v[130:131], v[16:17] op_sel_hi:[0,1]
	v_mul_f32_e32 v179, v179, v130
